# kept version with the K-loop barriers shifted 4 MFMAs into each MFMA cluster (head and tail) to overlap barrier latency with matrix work
# baseline (speedup 1.0000x reference)
; #define PG8_STAGE(bufoff, gbase, voff) do { _Pragma("unroll") for (int _i = 0; _i < 2; ++_i) \
;         __builtin_amdgcn_global_load_lds((const unsigned*)((const char*)(gbase) + (voff)[_i]), (PG8_LAS unsigned*)(lds + (bufoff) + ldsw + _i * 8192), 16, 0, 0); } while (0)
; #define PG8_LDA(dst, b, h) do { _Pragma("unroll") for (int m = 0; m < 4; ++m) _Pragma("unroll") for (int k = 0; k < 2; ++k) dst[m][k] = *(const PG8_LAS bf16x8*)(lds + PG8_SA(b, h) + aoff + m * 2048 + k * 1024); } while (0)
; #define PG8_LDB(dst, b, h) do { _Pragma("unroll") for (int n = 0; n < 2; ++n) _Pragma("unroll") for (int k = 0; k < 2; ++k) dst[n][k] = *(const PG8_LAS bf16x8*)(lds + PG8_SB(b, h) + boff + n * 2048 + k * 1024); } while (0)
; #define PG8_MMA(ai, bj, At, Bt) do { __builtin_amdgcn_s_setprio(1); _Pragma("unroll") for (int m = 0; m < 4; ++m) _Pragma("unroll") for (int n = 0; n < 2; ++n) _Pragma("unroll") for (int k = 0; k < 2; ++k) \
;         acc[ai][bj][m][n] = __builtin_amdgcn_mfma_f32_16x16x32_bf16(Bt[n][k], At[m][k], acc[ai][bj][m][n], 0, 0, 0); __builtin_amdgcn_s_setprio(0); } while (0)
; #define PG8_WAIT_V(n) asm volatile("s_waitcnt vmcnt(" #n ")" ::: "memory")
; #define PG8_WAIT_L(n) asm volatile("s_waitcnt lgkmcnt(" #n ")" ::: "memory")
; #define PG8_BAR __builtin_amdgcn_s_barrier()
; #define PG8_SCHED __builtin_amdgcn_sched_barrier(0)
; template <class Epi, class Sched, bool ALIGN_EPI = false, bool SP2 = false>
; __device__ __forceinline__ void gemm_phase(PG8_LAS unsigned char* lds, const Gemm g, const Sched& S, const Epi& E) {
;     ...
;             PG8_LDB(B0, 0, 0); PG8_LDB(B1, 0, 1); PG8_SCHED; PG8_LDA(At, 0, 0); PG8_STAGE(PG8_SA(1, 1), a1 + hstep, voffA);
;             PG8_WAIT_V(8); PG8_WAIT_L(0); PG8_BAR; PG8_MMA(0, 0, At, B0); PG8_MMA(0, 1, At, B1); PG8_BAR; PG8_SCHED;
;             PG8_LDA(At, 0, 1); PG8_STAGE(PG8_SB(0, 0), b2, voffB); PG8_STAGE(PG8_SB(0, 1), b2 + hstep, voffB); PG8_STAGE(PG8_SA(0, 0), a2, voffA);
;             PG8_WAIT_V(8); PG8_WAIT_L(0); PG8_BAR; PG8_MMA(1, 0, At, B0); PG8_MMA(1, 1, At, B1); PG8_BAR; PG8_SCHED;
.LBB0_411:
	ds_read_b128 v[130:133], v218
	ds_read_b128 v[134:137], v218 offset:1024
	ds_read_b128 v[138:141], v218 offset:2048
	ds_read_b128 v[142:145], v218 offset:3072
	ds_read_b128 v[146:149], v219
	ds_read_b128 v[150:153], v219 offset:1024
	ds_read_b128 v[154:157], v219 offset:2048
	ds_read_b128 v[158:161], v219 offset:3072
	s_add_u32 s6, s4, 0xfffc0080
	s_addc_u32 s7, s5, -1
	s_cmp_eq_u32 s37, 12
	s_cselect_b32 s45, s0, s7
	s_cselect_b32 s44, s1, s6
	s_cselect_b32 s7, s9, s35
	s_cselect_b32 s6, s12, s33
	v_lshl_add_u64 v[226:227], s[4:5], 0, v[188:189]
	s_add_i32 m0, s51, 0xc000
	s_waitcnt vmcnt(0)
	ds_read_b128 v[162:165], v220
	ds_read_b128 v[166:169], v220 offset:1024
	ds_read_b128 v[170:173], v220 offset:2048
	ds_read_b128 v[196:199], v220 offset:3072
	ds_read_b128 v[200:203], v220 offset:4096
	ds_read_b128 v[204:207], v220 offset:5120
	ds_read_b128 v[208:211], v220 offset:6144
	ds_read_b128 v[212:215], v220 offset:7168
	global_load_lds_dwordx4 v[226:227], off
	v_lshl_add_u64 v[226:227], s[4:5], 0, v[190:191]
	s_add_i32 m0, s51, 0xe000
	s_nop 0
	global_load_lds_dwordx4 v[226:227], off
	s_waitcnt vmcnt(8)
	s_waitcnt lgkmcnt(0)
	s_setprio 1
	s_waitcnt lgkmcnt(0)
	v_mfma_f32_16x16x32_bf16 v[126:129], v[130:133], v[162:165], v[126:129]
	v_mfma_f32_16x16x32_bf16 v[122:125], v[138:141], v[162:165], v[122:125]
	v_mfma_f32_16x16x32_bf16 v[110:113], v[130:133], v[170:173], v[110:113]
	v_mfma_f32_16x16x32_bf16 v[106:109], v[138:141], v[170:173], v[106:109]
	s_barrier
	v_mfma_f32_16x16x32_bf16 v[94:97], v[130:133], v[200:203], v[94:97]
	v_mfma_f32_16x16x32_bf16 v[90:93], v[138:141], v[200:203], v[90:93]
	v_mfma_f32_16x16x32_bf16 v[78:81], v[130:133], v[208:211], v[78:81]
	v_mfma_f32_16x16x32_bf16 v[74:77], v[138:141], v[208:211], v[74:77]
	v_mfma_f32_16x16x32_bf16 v[126:129], v[134:137], v[166:169], v[126:129]
	v_mfma_f32_16x16x32_bf16 v[122:125], v[142:145], v[166:169], v[122:125]
	v_mfma_f32_16x16x32_bf16 v[110:113], v[134:137], v[196:199], v[110:113]
	v_mfma_f32_16x16x32_bf16 v[106:109], v[142:145], v[196:199], v[106:109]
	v_mfma_f32_16x16x32_bf16 v[94:97], v[134:137], v[204:207], v[94:97]
	v_mfma_f32_16x16x32_bf16 v[90:93], v[142:145], v[204:207], v[90:93]
	v_mfma_f32_16x16x32_bf16 v[78:81], v[134:137], v[212:215], v[78:81]
	v_mfma_f32_16x16x32_bf16 v[74:77], v[142:145], v[212:215], v[74:77]
	s_setprio 0
	s_setprio 1
	v_mfma_f32_16x16x32_bf16 v[118:121], v[146:149], v[162:165], v[118:121]
	v_mfma_f32_16x16x32_bf16 v[114:117], v[154:157], v[162:165], v[114:117]
	v_mfma_f32_16x16x32_bf16 v[102:105], v[146:149], v[170:173], v[102:105]
	v_mfma_f32_16x16x32_bf16 v[98:101], v[154:157], v[170:173], v[98:101]
	v_mfma_f32_16x16x32_bf16 v[86:89], v[146:149], v[200:203], v[86:89]
	v_mfma_f32_16x16x32_bf16 v[82:85], v[154:157], v[200:203], v[82:85]
	v_mfma_f32_16x16x32_bf16 v[70:73], v[146:149], v[208:211], v[70:73]
	v_mfma_f32_16x16x32_bf16 v[66:69], v[154:157], v[208:211], v[66:69]
	v_mfma_f32_16x16x32_bf16 v[118:121], v[150:153], v[166:169], v[118:121]
	v_mfma_f32_16x16x32_bf16 v[114:117], v[158:161], v[166:169], v[114:117]
	v_mfma_f32_16x16x32_bf16 v[102:105], v[150:153], v[196:199], v[102:105]
	v_mfma_f32_16x16x32_bf16 v[98:101], v[158:161], v[196:199], v[98:101]
	s_barrier
	v_mfma_f32_16x16x32_bf16 v[86:89], v[150:153], v[204:207], v[86:89]
	v_mfma_f32_16x16x32_bf16 v[82:85], v[158:161], v[204:207], v[82:85]
	v_mfma_f32_16x16x32_bf16 v[70:73], v[150:153], v[212:215], v[70:73]
	v_mfma_f32_16x16x32_bf16 v[66:69], v[158:161], v[212:215], v[66:69]
	s_setprio 0
	s_add_i32 s43, s86, s50
	v_lshl_add_u64 v[226:227], s[6:7], 0, v[178:179]
	s_mov_b32 m0, s43
	ds_read_b128 v[162:165], v220 offset:16384
	ds_read_b128 v[166:169], v220 offset:17408
	ds_read_b128 v[170:173], v220 offset:18432
	ds_read_b128 v[196:199], v220 offset:19456
	ds_read_b128 v[200:203], v220 offset:20480
	ds_read_b128 v[204:207], v220 offset:21504
	ds_read_b128 v[208:211], v220 offset:22528
	ds_read_b128 v[212:215], v220 offset:23552
	global_load_lds_dwordx4 v[226:227], off
	s_add_i32 m0, s43, 0x2000
	s_add_u32 s46, s6, 0x40000
	v_lshl_add_u64 v[228:229], s[6:7], 0, v[182:183]
	s_addc_u32 s47, s7, 0
	s_add_i32 s43, s87, s50
	global_load_lds_dwordx4 v[228:229], off
	v_lshl_add_u64 v[230:231], s[46:47], 0, v[178:179]
	s_mov_b32 m0, s43
	v_lshl_add_u64 v[232:233], s[44:45], 0, v[180:181]
	global_load_lds_dwordx4 v[230:231], off
	v_lshl_add_u64 v[230:231], s[46:47], 0, v[182:183]
	s_add_i32 m0, s43, 0x2000
	s_nop 0
	global_load_lds_dwordx4 v[230:231], off
	v_lshl_add_u64 v[230:231], s[44:45], 0, v[176:177]
	s_mov_b32 m0, s51
	s_nop 0
	global_load_lds_dwordx4 v[230:231], off
	s_mov_b32 m0, s52
	s_nop 0
	global_load_lds_dwordx4 v[232:233], off
	s_waitcnt vmcnt(8)
	s_waitcnt lgkmcnt(0)
	s_setprio 1
	s_waitcnt lgkmcnt(0)
	v_mfma_f32_16x16x32_bf16 v[62:65], v[130:133], v[162:165], v[62:65]
	v_mfma_f32_16x16x32_bf16 v[58:61], v[138:141], v[162:165], v[58:61]
	v_mfma_f32_16x16x32_bf16 v[46:49], v[130:133], v[170:173], v[46:49]
	v_mfma_f32_16x16x32_bf16 v[42:45], v[138:141], v[170:173], v[42:45]
	s_barrier
; #define PG8_STAGE(bufoff, gbase, voff) do { _Pragma("unroll") for (int _i = 0; _i < 2; ++_i) \
;         __builtin_amdgcn_global_load_lds((const unsigned*)((const char*)(gbase) + (voff)[_i]), (PG8_LAS unsigned*)(lds + (bufoff) + ldsw + _i * 8192), 16, 0, 0); } while (0)
; #define PG8_LDA(dst, b, h) do { _Pragma("unroll") for (int m = 0; m < 4; ++m) _Pragma("unroll") for (int k = 0; k < 2; ++k) dst[m][k] = *(const PG8_LAS bf16x8*)(lds + PG8_SA(b, h) + aoff + m * 2048 + k * 1024); } while (0)
; #define PG8_LDB(dst, b, h) do { _Pragma("unroll") for (int n = 0; n < 2; ++n) _Pragma("unroll") for (int k = 0; k < 2; ++k) dst[n][k] = *(const PG8_LAS bf16x8*)(lds + PG8_SB(b, h) + boff + n * 2048 + k * 1024); } while (0)
; #define PG8_MMA(ai, bj, At, Bt) do { __builtin_amdgcn_s_setprio(1); _Pragma("unroll") for (int m = 0; m < 4; ++m) _Pragma("unroll") for (int n = 0; n < 2; ++n) _Pragma("unroll") for (int k = 0; k < 2; ++k) \
;         acc[ai][bj][m][n] = __builtin_amdgcn_mfma_f32_16x16x32_bf16(Bt[n][k], At[m][k], acc[ai][bj][m][n], 0, 0, 0); __builtin_amdgcn_s_setprio(0); } while (0)
; #define PG8_WAIT_V(n) asm volatile("s_waitcnt vmcnt(" #n ")" ::: "memory")
; #define PG8_WAIT_L(n) asm volatile("s_waitcnt lgkmcnt(" #n ")" ::: "memory")
; #define PG8_BAR __builtin_amdgcn_s_barrier()
; #define PG8_SCHED __builtin_amdgcn_sched_barrier(0)
; template <class Epi, class Sched, bool ALIGN_EPI = false, bool SP2 = false>
; __device__ __forceinline__ void gemm_phase(PG8_LAS unsigned char* lds, const Gemm g, const Sched& S, const Epi& E) {
;     ...
;             PG8_WAIT_V(8); PG8_WAIT_L(0); PG8_BAR; PG8_MMA(1, 0, At, B0); PG8_MMA(1, 1, At, B1); PG8_BAR; PG8_SCHED;
;             PG8_LDB(B0, 1, 0); PG8_LDB(B1, 1, 1); PG8_SCHED; PG8_LDA(At, 1, 0); PG8_STAGE(PG8_SA(0, 1), a2 + hstep, voffA);
;             PG8_WAIT_V(8); PG8_WAIT_L(0); PG8_BAR; PG8_MMA(0, 0, At, B0); PG8_MMA(0, 1, At, B1); PG8_BAR; PG8_SCHED;
	v_mfma_f32_16x16x32_bf16 v[30:33], v[130:133], v[200:203], v[30:33]
	v_mfma_f32_16x16x32_bf16 v[26:29], v[138:141], v[200:203], v[26:29]
	v_mfma_f32_16x16x32_bf16 v[14:17], v[130:133], v[208:211], v[14:17]
	v_mfma_f32_16x16x32_bf16 v[10:13], v[138:141], v[208:211], v[10:13]
	v_mfma_f32_16x16x32_bf16 v[62:65], v[134:137], v[166:169], v[62:65]
	v_mfma_f32_16x16x32_bf16 v[58:61], v[142:145], v[166:169], v[58:61]
	v_mfma_f32_16x16x32_bf16 v[46:49], v[134:137], v[196:199], v[46:49]
	v_mfma_f32_16x16x32_bf16 v[42:45], v[142:145], v[196:199], v[42:45]
	v_mfma_f32_16x16x32_bf16 v[30:33], v[134:137], v[204:207], v[30:33]
	v_mfma_f32_16x16x32_bf16 v[26:29], v[142:145], v[204:207], v[26:29]
	v_mfma_f32_16x16x32_bf16 v[14:17], v[134:137], v[212:215], v[14:17]
	v_mfma_f32_16x16x32_bf16 v[10:13], v[142:145], v[212:215], v[10:13]
	s_setprio 0
	s_setprio 1
	v_mfma_f32_16x16x32_bf16 v[54:57], v[146:149], v[162:165], v[54:57]
	v_mfma_f32_16x16x32_bf16 v[50:53], v[154:157], v[162:165], v[50:53]
	v_mfma_f32_16x16x32_bf16 v[38:41], v[146:149], v[170:173], v[38:41]
	v_mfma_f32_16x16x32_bf16 v[34:37], v[154:157], v[170:173], v[34:37]
	v_mfma_f32_16x16x32_bf16 v[22:25], v[146:149], v[200:203], v[22:25]
	v_mfma_f32_16x16x32_bf16 v[18:21], v[154:157], v[200:203], v[18:21]
	v_mfma_f32_16x16x32_bf16 v[6:9], v[146:149], v[208:211], v[6:9]
	v_mfma_f32_16x16x32_bf16 v[2:5], v[154:157], v[208:211], v[2:5]
	v_mfma_f32_16x16x32_bf16 v[54:57], v[150:153], v[166:169], v[54:57]
	v_mfma_f32_16x16x32_bf16 v[50:53], v[158:161], v[166:169], v[50:53]
	v_mfma_f32_16x16x32_bf16 v[38:41], v[150:153], v[196:199], v[38:41]
	v_mfma_f32_16x16x32_bf16 v[34:37], v[158:161], v[196:199], v[34:37]
	s_barrier
	v_mfma_f32_16x16x32_bf16 v[22:25], v[150:153], v[204:207], v[22:25]
	v_mfma_f32_16x16x32_bf16 v[18:21], v[158:161], v[204:207], v[18:21]
	v_mfma_f32_16x16x32_bf16 v[6:9], v[150:153], v[212:215], v[6:9]
	v_mfma_f32_16x16x32_bf16 v[2:5], v[158:161], v[212:215], v[2:5]
	s_setprio 0
	s_add_i32 s43, 0, 0x18000
	s_add_i32 s46, 0, 0x1c000
	v_add_u32_e32 v142, s43, v217
	v_add_u32_e32 v158, s46, v217
	ds_read_b128 v[130:133], v142
	ds_read_b128 v[134:137], v142 offset:1024
	ds_read_b128 v[138:141], v142 offset:2048
	ds_read_b128 v[142:145], v142 offset:3072
	ds_read_b128 v[146:149], v158
	ds_read_b128 v[150:153], v158 offset:1024
	ds_read_b128 v[154:157], v158 offset:2048
	ds_read_b128 v[158:161], v158 offset:3072
	s_add_u32 s44, s44, 0x40000
	s_addc_u32 s45, s45, 0
	s_mov_b32 m0, s53
	v_lshl_add_u64 v[234:235], s[44:45], 0, v[176:177]
	ds_read_b128 v[162:165], v220 offset:32768
	ds_read_b128 v[166:169], v220 offset:33792
	ds_read_b128 v[170:173], v220 offset:34816
	ds_read_b128 v[196:199], v220 offset:35840
	ds_read_b128 v[200:203], v220 offset:36864
	ds_read_b128 v[204:207], v220 offset:37888
	ds_read_b128 v[208:211], v220 offset:38912
	ds_read_b128 v[212:215], v220 offset:39936
	global_load_lds_dwordx4 v[234:235], off
	v_lshl_add_u64 v[234:235], s[44:45], 0, v[180:181]
	s_mov_b32 m0, s54
	s_nop 0
	global_load_lds_dwordx4 v[234:235], off
	s_waitcnt vmcnt(8)
	s_waitcnt lgkmcnt(0)
	s_setprio 1
	s_waitcnt lgkmcnt(0)
	v_mfma_f32_16x16x32_bf16 v[126:129], v[130:133], v[162:165], v[126:129]
	v_mfma_f32_16x16x32_bf16 v[122:125], v[138:141], v[162:165], v[122:125]
	v_mfma_f32_16x16x32_bf16 v[110:113], v[130:133], v[170:173], v[110:113]
	v_mfma_f32_16x16x32_bf16 v[106:109], v[138:141], v[170:173], v[106:109]
	s_barrier
	v_mfma_f32_16x16x32_bf16 v[94:97], v[130:133], v[200:203], v[94:97]
	v_mfma_f32_16x16x32_bf16 v[90:93], v[138:141], v[200:203], v[90:93]
	v_mfma_f32_16x16x32_bf16 v[78:81], v[130:133], v[208:211], v[78:81]
	v_mfma_f32_16x16x32_bf16 v[74:77], v[138:141], v[208:211], v[74:77]
	v_mfma_f32_16x16x32_bf16 v[126:129], v[134:137], v[166:169], v[126:129]
	v_mfma_f32_16x16x32_bf16 v[122:125], v[142:145], v[166:169], v[122:125]
	v_mfma_f32_16x16x32_bf16 v[110:113], v[134:137], v[196:199], v[110:113]
	v_mfma_f32_16x16x32_bf16 v[106:109], v[142:145], v[196:199], v[106:109]
	v_mfma_f32_16x16x32_bf16 v[94:97], v[134:137], v[204:207], v[94:97]
	v_mfma_f32_16x16x32_bf16 v[90:93], v[142:145], v[204:207], v[90:93]
	v_mfma_f32_16x16x32_bf16 v[78:81], v[134:137], v[212:215], v[78:81]
	v_mfma_f32_16x16x32_bf16 v[74:77], v[142:145], v[212:215], v[74:77]
	s_setprio 0
	s_setprio 1
	v_mfma_f32_16x16x32_bf16 v[118:121], v[146:149], v[162:165], v[118:121]
	v_mfma_f32_16x16x32_bf16 v[114:117], v[154:157], v[162:165], v[114:117]
	v_mfma_f32_16x16x32_bf16 v[102:105], v[146:149], v[170:173], v[102:105]
	v_mfma_f32_16x16x32_bf16 v[98:101], v[154:157], v[170:173], v[98:101]
	v_mfma_f32_16x16x32_bf16 v[86:89], v[146:149], v[200:203], v[86:89]
	v_mfma_f32_16x16x32_bf16 v[82:85], v[154:157], v[200:203], v[82:85]
	v_mfma_f32_16x16x32_bf16 v[70:73], v[146:149], v[208:211], v[70:73]
	v_mfma_f32_16x16x32_bf16 v[66:69], v[154:157], v[208:211], v[66:69]
	v_mfma_f32_16x16x32_bf16 v[118:121], v[150:153], v[166:169], v[118:121]
	v_mfma_f32_16x16x32_bf16 v[114:117], v[158:161], v[166:169], v[114:117]
	v_mfma_f32_16x16x32_bf16 v[102:105], v[150:153], v[196:199], v[102:105]
	v_mfma_f32_16x16x32_bf16 v[98:101], v[158:161], v[196:199], v[98:101]
	s_barrier
; #define PG8_STAGE(bufoff, gbase, voff) do { _Pragma("unroll") for (int _i = 0; _i < 2; ++_i) \
;         __builtin_amdgcn_global_load_lds((const unsigned*)((const char*)(gbase) + (voff)[_i]), (PG8_LAS unsigned*)(lds + (bufoff) + ldsw + _i * 8192), 16, 0, 0); } while (0)
; #define PG8_LDA(dst, b, h) do { _Pragma("unroll") for (int m = 0; m < 4; ++m) _Pragma("unroll") for (int k = 0; k < 2; ++k) dst[m][k] = *(const PG8_LAS bf16x8*)(lds + PG8_SA(b, h) + aoff + m * 2048 + k * 1024); } while (0)
; #define PG8_MMA(ai, bj, At, Bt) do { __builtin_amdgcn_s_setprio(1); _Pragma("unroll") for (int m = 0; m < 4; ++m) _Pragma("unroll") for (int n = 0; n < 2; ++n) _Pragma("unroll") for (int k = 0; k < 2; ++k) \
;         acc[ai][bj][m][n] = __builtin_amdgcn_mfma_f32_16x16x32_bf16(Bt[n][k], At[m][k], acc[ai][bj][m][n], 0, 0, 0); __builtin_amdgcn_s_setprio(0); } while (0)
; #define PG8_WAIT_V(n) asm volatile("s_waitcnt vmcnt(" #n ")" ::: "memory")
; #define PG8_WAIT_L(n) asm volatile("s_waitcnt lgkmcnt(" #n ")" ::: "memory")
; #define PG8_BAR __builtin_amdgcn_s_barrier()
; #define PG8_SCHED __builtin_amdgcn_sched_barrier(0)
; template <class Epi, class Sched, bool ALIGN_EPI = false, bool SP2 = false>
; __device__ __forceinline__ void gemm_phase(PG8_LAS unsigned char* lds, const Gemm g, const Sched& S, const Epi& E) {
;     ...
;             PG8_WAIT_V(8); PG8_WAIT_L(0); PG8_BAR; PG8_MMA(0, 0, At, B0); PG8_MMA(0, 1, At, B1); PG8_BAR; PG8_SCHED;
;             PG8_LDA(At, 1, 1); PG8_STAGE(PG8_SB(1, 0), b3, voffB); PG8_STAGE(PG8_SB(1, 1), b3 + hstep, voffB); PG8_STAGE(PG8_SA(1, 0), a3, voffA);
;             PG8_WAIT_V(8); PG8_WAIT_L(0); PG8_BAR; PG8_MMA(1, 0, At, B0); PG8_MMA(1, 1, At, B1); PG8_BAR; PG8_SCHED;
;     ...
;         if constexpr (ALIGN_EPI) { if (wr == 0) PG8_BAR; }
	v_mfma_f32_16x16x32_bf16 v[86:89], v[150:153], v[204:207], v[86:89]
	v_mfma_f32_16x16x32_bf16 v[82:85], v[158:161], v[204:207], v[82:85]
	v_mfma_f32_16x16x32_bf16 v[70:73], v[150:153], v[212:215], v[70:73]
	v_mfma_f32_16x16x32_bf16 v[66:69], v[158:161], v[212:215], v[66:69]
	s_setprio 0
	s_add_i32 s43, s43, s50
	v_lshl_add_u64 v[226:227], v[226:227], 0, s[20:21]
	s_mov_b32 m0, s43
	ds_read_b128 v[162:165], v220 offset:49152
	ds_read_b128 v[166:169], v220 offset:50176
	ds_read_b128 v[170:173], v220 offset:51200
	ds_read_b128 v[196:199], v220 offset:52224
	ds_read_b128 v[200:203], v220 offset:53248
	ds_read_b128 v[204:207], v220 offset:54272
	ds_read_b128 v[208:211], v220 offset:55296
	ds_read_b128 v[212:215], v220 offset:56320
	global_load_lds_dwordx4 v[226:227], off
	s_add_i32 m0, s43, 0x2000
	s_add_u32 s6, s6, 0x40080
	v_lshl_add_u64 v[226:227], v[228:229], 0, s[20:21]
	s_addc_u32 s7, s7, 0
	s_add_i32 s43, s46, s50
	global_load_lds_dwordx4 v[226:227], off
	v_lshl_add_u64 v[226:227], s[6:7], 0, v[178:179]
	s_mov_b32 m0, s43
	s_nop 0
	global_load_lds_dwordx4 v[226:227], off
	v_lshl_add_u64 v[226:227], s[6:7], 0, v[182:183]
	s_add_i32 m0, s43, 0x2000
	s_nop 0
	global_load_lds_dwordx4 v[226:227], off
	v_lshl_add_u64 v[226:227], v[230:231], 0, s[20:21]
	s_mov_b32 m0, s67
	s_nop 0
	global_load_lds_dwordx4 v[226:227], off
	v_lshl_add_u64 v[226:227], v[232:233], 0, s[20:21]
	s_mov_b32 m0, s68
	s_nop 0
	global_load_lds_dwordx4 v[226:227], off
	s_waitcnt vmcnt(8)
	s_waitcnt lgkmcnt(0)
	s_setprio 1
	s_waitcnt lgkmcnt(0)
	v_mfma_f32_16x16x32_bf16 v[62:65], v[130:133], v[162:165], v[62:65]
	v_mfma_f32_16x16x32_bf16 v[58:61], v[138:141], v[162:165], v[58:61]
	v_mfma_f32_16x16x32_bf16 v[46:49], v[130:133], v[170:173], v[46:49]
	v_mfma_f32_16x16x32_bf16 v[42:45], v[138:141], v[170:173], v[42:45]
	s_barrier
	v_mfma_f32_16x16x32_bf16 v[30:33], v[130:133], v[200:203], v[30:33]
	v_mfma_f32_16x16x32_bf16 v[26:29], v[138:141], v[200:203], v[26:29]
	v_mfma_f32_16x16x32_bf16 v[14:17], v[130:133], v[208:211], v[14:17]
	v_mfma_f32_16x16x32_bf16 v[10:13], v[138:141], v[208:211], v[10:13]
	v_mfma_f32_16x16x32_bf16 v[62:65], v[134:137], v[166:169], v[62:65]
	v_mfma_f32_16x16x32_bf16 v[58:61], v[142:145], v[166:169], v[58:61]
	v_mfma_f32_16x16x32_bf16 v[46:49], v[134:137], v[196:199], v[46:49]
	v_mfma_f32_16x16x32_bf16 v[42:45], v[142:145], v[196:199], v[42:45]
	v_mfma_f32_16x16x32_bf16 v[30:33], v[134:137], v[204:207], v[30:33]
	v_mfma_f32_16x16x32_bf16 v[26:29], v[142:145], v[204:207], v[26:29]
	v_mfma_f32_16x16x32_bf16 v[14:17], v[134:137], v[212:215], v[14:17]
	v_mfma_f32_16x16x32_bf16 v[10:13], v[142:145], v[212:215], v[10:13]
	s_setprio 0
	s_setprio 1
	v_mfma_f32_16x16x32_bf16 v[54:57], v[146:149], v[162:165], v[54:57]
	v_mfma_f32_16x16x32_bf16 v[50:53], v[154:157], v[162:165], v[50:53]
	v_mfma_f32_16x16x32_bf16 v[38:41], v[146:149], v[170:173], v[38:41]
	v_mfma_f32_16x16x32_bf16 v[34:37], v[154:157], v[170:173], v[34:37]
	v_mfma_f32_16x16x32_bf16 v[22:25], v[146:149], v[200:203], v[22:25]
	v_mfma_f32_16x16x32_bf16 v[18:21], v[154:157], v[200:203], v[18:21]
	v_mfma_f32_16x16x32_bf16 v[6:9], v[146:149], v[208:211], v[6:9]
	v_mfma_f32_16x16x32_bf16 v[2:5], v[154:157], v[208:211], v[2:5]
	v_mfma_f32_16x16x32_bf16 v[54:57], v[150:153], v[166:169], v[54:57]
	v_mfma_f32_16x16x32_bf16 v[50:53], v[158:161], v[166:169], v[50:53]
	v_mfma_f32_16x16x32_bf16 v[38:41], v[150:153], v[196:199], v[38:41]
	v_mfma_f32_16x16x32_bf16 v[34:37], v[158:161], v[196:199], v[34:37]
	s_barrier
	v_mfma_f32_16x16x32_bf16 v[22:25], v[150:153], v[204:207], v[22:25]
	v_mfma_f32_16x16x32_bf16 v[18:21], v[158:161], v[204:207], v[18:21]
	v_mfma_f32_16x16x32_bf16 v[6:9], v[150:153], v[212:215], v[6:9]
	v_mfma_f32_16x16x32_bf16 v[2:5], v[158:161], v[212:215], v[2:5]
	s_setprio 0
	s_add_i32 s37, s37, 2
	s_add_u32 s4, s4, 0x100
	s_addc_u32 s5, s5, 0
	s_add_u32 s33, s33, 0x100
	s_addc_u32 s35, s35, 0
	s_cmp_gt_u32 s37, 13
	s_cbranch_scc0 .LBB0_411
	s_and_b64 vcc, exec, s[22:23]
	s_cbranch_vccz .LBB0_414
	s_barrier

; #define PG8_STAGE(bufoff, gbase, voff) do { _Pragma("unroll") for (int _i = 0; _i < 2; ++_i) \
;         __builtin_amdgcn_global_load_lds((const unsigned*)((const char*)(gbase) + (voff)[_i]), (PG8_LAS unsigned*)(lds + (bufoff) + ldsw + _i * 8192), 16, 0, 0); } while (0)
; #define PG8_LDA(dst, b, h) do { _Pragma("unroll") for (int m = 0; m < 4; ++m) _Pragma("unroll") for (int k = 0; k < 2; ++k) dst[m][k] = *(const PG8_LAS bf16x8*)(lds + PG8_SA(b, h) + aoff + m * 2048 + k * 1024); } while (0)
; #define PG8_LDB(dst, b, h) do { _Pragma("unroll") for (int n = 0; n < 2; ++n) _Pragma("unroll") for (int k = 0; k < 2; ++k) dst[n][k] = *(const PG8_LAS bf16x8*)(lds + PG8_SB(b, h) + boff + n * 2048 + k * 1024); } while (0)
; #define PG8_MMA(ai, bj, At, Bt) do { __builtin_amdgcn_s_setprio(1); _Pragma("unroll") for (int m = 0; m < 4; ++m) _Pragma("unroll") for (int n = 0; n < 2; ++n) _Pragma("unroll") for (int k = 0; k < 2; ++k) \
;         acc[ai][bj][m][n] = __builtin_amdgcn_mfma_f32_16x16x32_bf16(Bt[n][k], At[m][k], acc[ai][bj][m][n], 0, 0, 0); __builtin_amdgcn_s_setprio(0); } while (0)
; #define PG8_WAIT_V(n) asm volatile("s_waitcnt vmcnt(" #n ")" ::: "memory")
; #define PG8_WAIT_L(n) asm volatile("s_waitcnt lgkmcnt(" #n ")" ::: "memory")
; #define PG8_BAR __builtin_amdgcn_s_barrier()
; #define PG8_SCHED __builtin_amdgcn_sched_barrier(0)
; template <class Epi, class Sched, bool ALIGN_EPI = false, bool SP2 = false>
; __device__ __forceinline__ void gemm_phase(PG8_LAS unsigned char* lds, const Gemm g, const Sched& S, const Epi& E) {
;     ...
;             PG8_LDB(B0, 0, 0); PG8_LDB(B1, 0, 1); PG8_SCHED; PG8_LDA(At, 0, 0); PG8_STAGE(PG8_SA(1, 1), a1 + hstep, voffA);
;             PG8_WAIT_V(8); PG8_WAIT_L(0); PG8_BAR; PG8_MMA(0, 0, At, B0); PG8_MMA(0, 1, At, B1); PG8_BAR; PG8_SCHED;
;             PG8_LDA(At, 0, 1); PG8_STAGE(PG8_SB(0, 0), b2, voffB); PG8_STAGE(PG8_SB(0, 1), b2 + hstep, voffB); PG8_STAGE(PG8_SA(0, 0), a2, voffA);
;             PG8_WAIT_V(8); PG8_WAIT_L(0); PG8_BAR; PG8_MMA(1, 0, At, B0); PG8_MMA(1, 1, At, B1); PG8_BAR; PG8_SCHED;
.LBB0_1236:
	ds_read_b128 v[128:131], v175
	ds_read_b128 v[132:135], v175 offset:1024
	ds_read_b128 v[136:139], v175 offset:2048
	ds_read_b128 v[140:143], v175 offset:3072
	ds_read_b128 v[144:147], v176
	ds_read_b128 v[148:151], v176 offset:1024
	ds_read_b128 v[164:167], v176 offset:2048
	ds_read_b128 v[168:171], v176 offset:3072
	s_add_u32 s24, s22, 0xfffc0080
	s_addc_u32 s25, s23, -1
	s_cmp_eq_u32 s61, 12
	s_cselect_b32 s27, s5, s25
	s_cselect_b32 s26, s6, s24
	s_cselect_b32 s25, s15, s60
	s_cselect_b32 s24, s17, s59
	v_lshl_add_u64 v[210:211], s[22:23], 0, v[156:157]
	s_add_i32 m0, s36, 0xc000
	ds_read_b128 v[178:181], v177
	ds_read_b128 v[182:185], v177 offset:1024
	ds_read_b128 v[186:189], v177 offset:2048
	ds_read_b128 v[190:193], v177 offset:3072
	ds_read_b128 v[194:197], v177 offset:4096
	ds_read_b128 v[198:201], v177 offset:5120
	ds_read_b128 v[202:205], v177 offset:6144
	ds_read_b128 v[206:209], v177 offset:7168
	global_load_lds_dwordx4 v[210:211], off
	v_lshl_add_u64 v[210:211], s[22:23], 0, v[158:159]
	s_add_i32 m0, s36, 0xe000
	s_nop 0
	global_load_lds_dwordx4 v[210:211], off
	s_waitcnt vmcnt(8)
	s_waitcnt lgkmcnt(0)
	s_setprio 1
	s_waitcnt lgkmcnt(0)
	v_mfma_f32_16x16x32_bf16 v[124:127], v[128:131], v[178:181], v[124:127]
	v_mfma_f32_16x16x32_bf16 v[120:123], v[136:139], v[178:181], v[120:123]
	v_mfma_f32_16x16x32_bf16 v[108:111], v[128:131], v[186:189], v[108:111]
	v_mfma_f32_16x16x32_bf16 v[104:107], v[136:139], v[186:189], v[104:107]
	s_barrier
	v_mfma_f32_16x16x32_bf16 v[92:95], v[128:131], v[194:197], v[92:95]
	v_mfma_f32_16x16x32_bf16 v[88:91], v[136:139], v[194:197], v[88:91]
	v_mfma_f32_16x16x32_bf16 v[76:79], v[128:131], v[202:205], v[76:79]
	v_mfma_f32_16x16x32_bf16 v[72:75], v[136:139], v[202:205], v[72:75]
	v_mfma_f32_16x16x32_bf16 v[124:127], v[132:135], v[182:185], v[124:127]
	v_mfma_f32_16x16x32_bf16 v[120:123], v[140:143], v[182:185], v[120:123]
	v_mfma_f32_16x16x32_bf16 v[108:111], v[132:135], v[190:193], v[108:111]
	v_mfma_f32_16x16x32_bf16 v[104:107], v[140:143], v[190:193], v[104:107]
	v_mfma_f32_16x16x32_bf16 v[92:95], v[132:135], v[198:201], v[92:95]
	v_mfma_f32_16x16x32_bf16 v[88:91], v[140:143], v[198:201], v[88:91]
	v_mfma_f32_16x16x32_bf16 v[76:79], v[132:135], v[206:209], v[76:79]
	v_mfma_f32_16x16x32_bf16 v[72:75], v[140:143], v[206:209], v[72:75]
	s_setprio 0
	s_setprio 1
	v_mfma_f32_16x16x32_bf16 v[116:119], v[144:147], v[178:181], v[116:119]
	v_mfma_f32_16x16x32_bf16 v[112:115], v[164:167], v[178:181], v[112:115]
	v_mfma_f32_16x16x32_bf16 v[100:103], v[144:147], v[186:189], v[100:103]
	v_mfma_f32_16x16x32_bf16 v[96:99], v[164:167], v[186:189], v[96:99]
	v_mfma_f32_16x16x32_bf16 v[84:87], v[144:147], v[194:197], v[84:87]
	v_mfma_f32_16x16x32_bf16 v[80:83], v[164:167], v[194:197], v[80:83]
	v_mfma_f32_16x16x32_bf16 v[68:71], v[144:147], v[202:205], v[68:71]
	v_mfma_f32_16x16x32_bf16 v[64:67], v[164:167], v[202:205], v[64:67]
	v_mfma_f32_16x16x32_bf16 v[116:119], v[148:151], v[182:185], v[116:119]
	v_mfma_f32_16x16x32_bf16 v[112:115], v[168:171], v[182:185], v[112:115]
	v_mfma_f32_16x16x32_bf16 v[100:103], v[148:151], v[190:193], v[100:103]
	v_mfma_f32_16x16x32_bf16 v[96:99], v[168:171], v[190:193], v[96:99]
	s_barrier
	v_mfma_f32_16x16x32_bf16 v[84:87], v[148:151], v[198:201], v[84:87]
	v_mfma_f32_16x16x32_bf16 v[80:83], v[168:171], v[198:201], v[80:83]
	v_mfma_f32_16x16x32_bf16 v[68:71], v[148:151], v[206:209], v[68:71]
	v_mfma_f32_16x16x32_bf16 v[64:67], v[168:171], v[206:209], v[64:67]
	s_setprio 0
	s_add_i32 s62, s52, s34
	v_lshl_add_u64 v[210:211], s[24:25], 0, v[152:153]
	s_mov_b32 m0, s62
	ds_read_b128 v[178:181], v177 offset:16384
	ds_read_b128 v[182:185], v177 offset:17408
	ds_read_b128 v[186:189], v177 offset:18432
	ds_read_b128 v[190:193], v177 offset:19456
	ds_read_b128 v[194:197], v177 offset:20480
	ds_read_b128 v[198:201], v177 offset:21504
	ds_read_b128 v[202:205], v177 offset:22528
	ds_read_b128 v[206:209], v177 offset:23552
	global_load_lds_dwordx4 v[210:211], off
	s_add_i32 m0, s62, 0x2000
	s_add_u32 s62, s24, 0x40000
	v_lshl_add_u64 v[212:213], s[24:25], 0, v[154:155]
	s_addc_u32 s63, s25, 0
	s_add_i32 s64, s53, s34
	global_load_lds_dwordx4 v[212:213], off
	v_lshl_add_u64 v[214:215], s[62:63], 0, v[152:153]
	s_mov_b32 m0, s64
	v_lshl_add_u64 v[216:217], s[26:27], 0, v[154:155]
	global_load_lds_dwordx4 v[214:215], off
	v_lshl_add_u64 v[214:215], s[62:63], 0, v[154:155]
	s_add_i32 m0, s64, 0x2000
	s_nop 0
	global_load_lds_dwordx4 v[214:215], off
	v_lshl_add_u64 v[214:215], s[26:27], 0, v[152:153]
	s_mov_b32 m0, s36
	s_nop 0
	global_load_lds_dwordx4 v[214:215], off
	s_mov_b32 m0, s37
	s_nop 0
	global_load_lds_dwordx4 v[216:217], off
	s_waitcnt vmcnt(8)
	s_waitcnt lgkmcnt(0)
	s_setprio 1
	s_waitcnt lgkmcnt(0)
	v_mfma_f32_16x16x32_bf16 v[60:63], v[128:131], v[178:181], v[60:63]
	v_mfma_f32_16x16x32_bf16 v[56:59], v[136:139], v[178:181], v[56:59]
	v_mfma_f32_16x16x32_bf16 v[44:47], v[128:131], v[186:189], v[44:47]
	v_mfma_f32_16x16x32_bf16 v[40:43], v[136:139], v[186:189], v[40:43]
	s_barrier
; #define PG8_STAGE(bufoff, gbase, voff) do { _Pragma("unroll") for (int _i = 0; _i < 2; ++_i) \
;         __builtin_amdgcn_global_load_lds((const unsigned*)((const char*)(gbase) + (voff)[_i]), (PG8_LAS unsigned*)(lds + (bufoff) + ldsw + _i * 8192), 16, 0, 0); } while (0)
; #define PG8_LDA(dst, b, h) do { _Pragma("unroll") for (int m = 0; m < 4; ++m) _Pragma("unroll") for (int k = 0; k < 2; ++k) dst[m][k] = *(const PG8_LAS bf16x8*)(lds + PG8_SA(b, h) + aoff + m * 2048 + k * 1024); } while (0)
; #define PG8_LDB(dst, b, h) do { _Pragma("unroll") for (int n = 0; n < 2; ++n) _Pragma("unroll") for (int k = 0; k < 2; ++k) dst[n][k] = *(const PG8_LAS bf16x8*)(lds + PG8_SB(b, h) + boff + n * 2048 + k * 1024); } while (0)
; #define PG8_MMA(ai, bj, At, Bt) do { __builtin_amdgcn_s_setprio(1); _Pragma("unroll") for (int m = 0; m < 4; ++m) _Pragma("unroll") for (int n = 0; n < 2; ++n) _Pragma("unroll") for (int k = 0; k < 2; ++k) \
;         acc[ai][bj][m][n] = __builtin_amdgcn_mfma_f32_16x16x32_bf16(Bt[n][k], At[m][k], acc[ai][bj][m][n], 0, 0, 0); __builtin_amdgcn_s_setprio(0); } while (0)
; #define PG8_WAIT_V(n) asm volatile("s_waitcnt vmcnt(" #n ")" ::: "memory")
; #define PG8_WAIT_L(n) asm volatile("s_waitcnt lgkmcnt(" #n ")" ::: "memory")
; #define PG8_BAR __builtin_amdgcn_s_barrier()
; #define PG8_SCHED __builtin_amdgcn_sched_barrier(0)
; template <class Epi, class Sched, bool ALIGN_EPI = false, bool SP2 = false>
; __device__ __forceinline__ void gemm_phase(PG8_LAS unsigned char* lds, const Gemm g, const Sched& S, const Epi& E) {
;     ...
;             PG8_WAIT_V(8); PG8_WAIT_L(0); PG8_BAR; PG8_MMA(1, 0, At, B0); PG8_MMA(1, 1, At, B1); PG8_BAR; PG8_SCHED;
;             PG8_LDB(B0, 1, 0); PG8_LDB(B1, 1, 1); PG8_SCHED; PG8_LDA(At, 1, 0); PG8_STAGE(PG8_SA(0, 1), a2 + hstep, voffA);
;             PG8_WAIT_V(8); PG8_WAIT_L(0); PG8_BAR; PG8_MMA(0, 0, At, B0); PG8_MMA(0, 1, At, B1); PG8_BAR; PG8_SCHED;
	v_mfma_f32_16x16x32_bf16 v[28:31], v[128:131], v[194:197], v[28:31]
	v_mfma_f32_16x16x32_bf16 v[24:27], v[136:139], v[194:197], v[24:27]
	v_mfma_f32_16x16x32_bf16 v[12:15], v[128:131], v[202:205], v[12:15]
	v_mfma_f32_16x16x32_bf16 v[8:11], v[136:139], v[202:205], v[8:11]
	v_mfma_f32_16x16x32_bf16 v[60:63], v[132:135], v[182:185], v[60:63]
	v_mfma_f32_16x16x32_bf16 v[56:59], v[140:143], v[182:185], v[56:59]
	v_mfma_f32_16x16x32_bf16 v[44:47], v[132:135], v[190:193], v[44:47]
	v_mfma_f32_16x16x32_bf16 v[40:43], v[140:143], v[190:193], v[40:43]
	v_mfma_f32_16x16x32_bf16 v[28:31], v[132:135], v[198:201], v[28:31]
	v_mfma_f32_16x16x32_bf16 v[24:27], v[140:143], v[198:201], v[24:27]
	v_mfma_f32_16x16x32_bf16 v[12:15], v[132:135], v[206:209], v[12:15]
	v_mfma_f32_16x16x32_bf16 v[8:11], v[140:143], v[206:209], v[8:11]
	s_setprio 0
	s_setprio 1
	v_mfma_f32_16x16x32_bf16 v[52:55], v[144:147], v[178:181], v[52:55]
	v_mfma_f32_16x16x32_bf16 v[48:51], v[164:167], v[178:181], v[48:51]
	v_mfma_f32_16x16x32_bf16 v[36:39], v[144:147], v[186:189], v[36:39]
	v_mfma_f32_16x16x32_bf16 v[32:35], v[164:167], v[186:189], v[32:35]
	v_mfma_f32_16x16x32_bf16 v[20:23], v[144:147], v[194:197], v[20:23]
	v_mfma_f32_16x16x32_bf16 v[16:19], v[164:167], v[194:197], v[16:19]
	v_mfma_f32_16x16x32_bf16 v[4:7], v[144:147], v[202:205], v[4:7]
	v_mfma_f32_16x16x32_bf16 v[0:3], v[164:167], v[202:205], v[0:3]
	v_mfma_f32_16x16x32_bf16 v[52:55], v[148:151], v[182:185], v[52:55]
	v_mfma_f32_16x16x32_bf16 v[48:51], v[168:171], v[182:185], v[48:51]
	v_mfma_f32_16x16x32_bf16 v[36:39], v[148:151], v[190:193], v[36:39]
	v_mfma_f32_16x16x32_bf16 v[32:35], v[168:171], v[190:193], v[32:35]
	s_barrier
	v_mfma_f32_16x16x32_bf16 v[20:23], v[148:151], v[198:201], v[20:23]
	v_mfma_f32_16x16x32_bf16 v[16:19], v[168:171], v[198:201], v[16:19]
	v_mfma_f32_16x16x32_bf16 v[4:7], v[148:151], v[206:209], v[4:7]
	v_mfma_f32_16x16x32_bf16 v[0:3], v[168:171], v[206:209], v[0:3]
	s_setprio 0
	s_add_i32 s62, 0, 0x18000
	s_add_i32 s63, 0, 0x1c000
	v_add_u32_e32 v140, s62, v174
	v_add_u32_e32 v168, s63, v174
	ds_read_b128 v[128:131], v140
	ds_read_b128 v[132:135], v140 offset:1024
	ds_read_b128 v[136:139], v140 offset:2048
	ds_read_b128 v[140:143], v140 offset:3072
	ds_read_b128 v[144:147], v168
	ds_read_b128 v[148:151], v168 offset:1024
	ds_read_b128 v[164:167], v168 offset:2048
	ds_read_b128 v[168:171], v168 offset:3072
	s_add_u32 s26, s26, 0x40000
	s_addc_u32 s27, s27, 0
	s_mov_b32 m0, s38
	v_lshl_add_u64 v[218:219], s[26:27], 0, v[152:153]
	ds_read_b128 v[178:181], v177 offset:32768
	ds_read_b128 v[182:185], v177 offset:33792
	ds_read_b128 v[186:189], v177 offset:34816
	ds_read_b128 v[190:193], v177 offset:35840
	ds_read_b128 v[194:197], v177 offset:36864
	ds_read_b128 v[198:201], v177 offset:37888
	ds_read_b128 v[202:205], v177 offset:38912
	ds_read_b128 v[206:209], v177 offset:39936
	global_load_lds_dwordx4 v[218:219], off
	v_lshl_add_u64 v[218:219], s[26:27], 0, v[154:155]
	s_mov_b32 m0, s39
	s_nop 0
	global_load_lds_dwordx4 v[218:219], off
	s_waitcnt vmcnt(8)
	s_waitcnt lgkmcnt(0)
	s_setprio 1
	s_waitcnt lgkmcnt(0)
	v_mfma_f32_16x16x32_bf16 v[124:127], v[128:131], v[178:181], v[124:127]
	v_mfma_f32_16x16x32_bf16 v[120:123], v[136:139], v[178:181], v[120:123]
	v_mfma_f32_16x16x32_bf16 v[108:111], v[128:131], v[186:189], v[108:111]
	v_mfma_f32_16x16x32_bf16 v[104:107], v[136:139], v[186:189], v[104:107]
	s_barrier
	v_mfma_f32_16x16x32_bf16 v[92:95], v[128:131], v[194:197], v[92:95]
	v_mfma_f32_16x16x32_bf16 v[88:91], v[136:139], v[194:197], v[88:91]
	v_mfma_f32_16x16x32_bf16 v[76:79], v[128:131], v[202:205], v[76:79]
	v_mfma_f32_16x16x32_bf16 v[72:75], v[136:139], v[202:205], v[72:75]
	v_mfma_f32_16x16x32_bf16 v[124:127], v[132:135], v[182:185], v[124:127]
	v_mfma_f32_16x16x32_bf16 v[120:123], v[140:143], v[182:185], v[120:123]
	v_mfma_f32_16x16x32_bf16 v[108:111], v[132:135], v[190:193], v[108:111]
	v_mfma_f32_16x16x32_bf16 v[104:107], v[140:143], v[190:193], v[104:107]
	v_mfma_f32_16x16x32_bf16 v[92:95], v[132:135], v[198:201], v[92:95]
	v_mfma_f32_16x16x32_bf16 v[88:91], v[140:143], v[198:201], v[88:91]
	v_mfma_f32_16x16x32_bf16 v[76:79], v[132:135], v[206:209], v[76:79]
	v_mfma_f32_16x16x32_bf16 v[72:75], v[140:143], v[206:209], v[72:75]
	s_setprio 0
	s_setprio 1
	v_mfma_f32_16x16x32_bf16 v[116:119], v[144:147], v[178:181], v[116:119]
	v_mfma_f32_16x16x32_bf16 v[112:115], v[164:167], v[178:181], v[112:115]
	v_mfma_f32_16x16x32_bf16 v[100:103], v[144:147], v[186:189], v[100:103]
	v_mfma_f32_16x16x32_bf16 v[96:99], v[164:167], v[186:189], v[96:99]
	v_mfma_f32_16x16x32_bf16 v[84:87], v[144:147], v[194:197], v[84:87]
	v_mfma_f32_16x16x32_bf16 v[80:83], v[164:167], v[194:197], v[80:83]
	v_mfma_f32_16x16x32_bf16 v[68:71], v[144:147], v[202:205], v[68:71]
	v_mfma_f32_16x16x32_bf16 v[64:67], v[164:167], v[202:205], v[64:67]
	v_mfma_f32_16x16x32_bf16 v[116:119], v[148:151], v[182:185], v[116:119]
	v_mfma_f32_16x16x32_bf16 v[112:115], v[168:171], v[182:185], v[112:115]
	v_mfma_f32_16x16x32_bf16 v[100:103], v[148:151], v[190:193], v[100:103]
	v_mfma_f32_16x16x32_bf16 v[96:99], v[168:171], v[190:193], v[96:99]
	s_barrier
; #define PG8_STAGE(bufoff, gbase, voff) do { _Pragma("unroll") for (int _i = 0; _i < 2; ++_i) \
;         __builtin_amdgcn_global_load_lds((const unsigned*)((const char*)(gbase) + (voff)[_i]), (PG8_LAS unsigned*)(lds + (bufoff) + ldsw + _i * 8192), 16, 0, 0); } while (0)
; #define PG8_LDA(dst, b, h) do { _Pragma("unroll") for (int m = 0; m < 4; ++m) _Pragma("unroll") for (int k = 0; k < 2; ++k) dst[m][k] = *(const PG8_LAS bf16x8*)(lds + PG8_SA(b, h) + aoff + m * 2048 + k * 1024); } while (0)
; #define PG8_MMA(ai, bj, At, Bt) do { __builtin_amdgcn_s_setprio(1); _Pragma("unroll") for (int m = 0; m < 4; ++m) _Pragma("unroll") for (int n = 0; n < 2; ++n) _Pragma("unroll") for (int k = 0; k < 2; ++k) \
;         acc[ai][bj][m][n] = __builtin_amdgcn_mfma_f32_16x16x32_bf16(Bt[n][k], At[m][k], acc[ai][bj][m][n], 0, 0, 0); __builtin_amdgcn_s_setprio(0); } while (0)
; #define PG8_WAIT_V(n) asm volatile("s_waitcnt vmcnt(" #n ")" ::: "memory")
; #define PG8_WAIT_L(n) asm volatile("s_waitcnt lgkmcnt(" #n ")" ::: "memory")
; #define PG8_BAR __builtin_amdgcn_s_barrier()
; #define PG8_SCHED __builtin_amdgcn_sched_barrier(0)
; template <class Epi, class Sched, bool ALIGN_EPI = false, bool SP2 = false>
; __device__ __forceinline__ void gemm_phase(PG8_LAS unsigned char* lds, const Gemm g, const Sched& S, const Epi& E) {
;     ...
;             PG8_WAIT_V(8); PG8_WAIT_L(0); PG8_BAR; PG8_MMA(0, 0, At, B0); PG8_MMA(0, 1, At, B1); PG8_BAR; PG8_SCHED;
;             PG8_LDA(At, 1, 1); PG8_STAGE(PG8_SB(1, 0), b3, voffB); PG8_STAGE(PG8_SB(1, 1), b3 + hstep, voffB); PG8_STAGE(PG8_SA(1, 0), a3, voffA);
;             PG8_WAIT_V(8); PG8_WAIT_L(0); PG8_BAR; PG8_MMA(1, 0, At, B0); PG8_MMA(1, 1, At, B1); PG8_BAR; PG8_SCHED;
;     ...
;         if constexpr (ALIGN_EPI) { if (wr == 0) PG8_BAR; }
	v_mfma_f32_16x16x32_bf16 v[84:87], v[148:151], v[198:201], v[84:87]
	v_mfma_f32_16x16x32_bf16 v[80:83], v[168:171], v[198:201], v[80:83]
	v_mfma_f32_16x16x32_bf16 v[68:71], v[148:151], v[206:209], v[68:71]
	v_mfma_f32_16x16x32_bf16 v[64:67], v[168:171], v[206:209], v[64:67]
	s_setprio 0
	s_add_i32 s26, s62, s34
	v_lshl_add_u64 v[210:211], v[210:211], 0, s[10:11]
	s_mov_b32 m0, s26
	ds_read_b128 v[178:181], v177 offset:49152
	ds_read_b128 v[182:185], v177 offset:50176
	ds_read_b128 v[186:189], v177 offset:51200
	ds_read_b128 v[190:193], v177 offset:52224
	ds_read_b128 v[194:197], v177 offset:53248
	ds_read_b128 v[198:201], v177 offset:54272
	ds_read_b128 v[202:205], v177 offset:55296
	ds_read_b128 v[206:209], v177 offset:56320
	global_load_lds_dwordx4 v[210:211], off
	s_add_i32 m0, s26, 0x2000
	s_add_u32 s24, s24, 0x40080
	v_lshl_add_u64 v[210:211], v[212:213], 0, s[10:11]
	s_addc_u32 s25, s25, 0
	s_add_i32 s26, s63, s34
	global_load_lds_dwordx4 v[210:211], off
	v_lshl_add_u64 v[210:211], s[24:25], 0, v[152:153]
	s_mov_b32 m0, s26
	s_nop 0
	global_load_lds_dwordx4 v[210:211], off
	v_lshl_add_u64 v[210:211], s[24:25], 0, v[154:155]
	s_add_i32 m0, s26, 0x2000
	s_nop 0
	global_load_lds_dwordx4 v[210:211], off
	v_lshl_add_u64 v[210:211], v[214:215], 0, s[10:11]
	s_mov_b32 m0, s45
	s_nop 0
	global_load_lds_dwordx4 v[210:211], off
	v_lshl_add_u64 v[210:211], v[216:217], 0, s[10:11]
	s_mov_b32 m0, s46
	s_nop 0
	global_load_lds_dwordx4 v[210:211], off
	s_waitcnt vmcnt(8)
	s_waitcnt lgkmcnt(0)
	s_setprio 1
	s_waitcnt lgkmcnt(0)
	v_mfma_f32_16x16x32_bf16 v[60:63], v[128:131], v[178:181], v[60:63]
	v_mfma_f32_16x16x32_bf16 v[56:59], v[136:139], v[178:181], v[56:59]
	v_mfma_f32_16x16x32_bf16 v[44:47], v[128:131], v[186:189], v[44:47]
	v_mfma_f32_16x16x32_bf16 v[40:43], v[136:139], v[186:189], v[40:43]
	s_barrier
	v_mfma_f32_16x16x32_bf16 v[28:31], v[128:131], v[194:197], v[28:31]
	v_mfma_f32_16x16x32_bf16 v[24:27], v[136:139], v[194:197], v[24:27]
	v_mfma_f32_16x16x32_bf16 v[12:15], v[128:131], v[202:205], v[12:15]
	v_mfma_f32_16x16x32_bf16 v[8:11], v[136:139], v[202:205], v[8:11]
	v_mfma_f32_16x16x32_bf16 v[60:63], v[132:135], v[182:185], v[60:63]
	v_mfma_f32_16x16x32_bf16 v[56:59], v[140:143], v[182:185], v[56:59]
	v_mfma_f32_16x16x32_bf16 v[44:47], v[132:135], v[190:193], v[44:47]
	v_mfma_f32_16x16x32_bf16 v[40:43], v[140:143], v[190:193], v[40:43]
	v_mfma_f32_16x16x32_bf16 v[28:31], v[132:135], v[198:201], v[28:31]
	v_mfma_f32_16x16x32_bf16 v[24:27], v[140:143], v[198:201], v[24:27]
	v_mfma_f32_16x16x32_bf16 v[12:15], v[132:135], v[206:209], v[12:15]
	v_mfma_f32_16x16x32_bf16 v[8:11], v[140:143], v[206:209], v[8:11]
	s_setprio 0
	s_setprio 1
	v_mfma_f32_16x16x32_bf16 v[52:55], v[144:147], v[178:181], v[52:55]
	v_mfma_f32_16x16x32_bf16 v[48:51], v[164:167], v[178:181], v[48:51]
	v_mfma_f32_16x16x32_bf16 v[36:39], v[144:147], v[186:189], v[36:39]
	v_mfma_f32_16x16x32_bf16 v[32:35], v[164:167], v[186:189], v[32:35]
	v_mfma_f32_16x16x32_bf16 v[20:23], v[144:147], v[194:197], v[20:23]
	v_mfma_f32_16x16x32_bf16 v[16:19], v[164:167], v[194:197], v[16:19]
	v_mfma_f32_16x16x32_bf16 v[4:7], v[144:147], v[202:205], v[4:7]
	v_mfma_f32_16x16x32_bf16 v[0:3], v[164:167], v[202:205], v[0:3]
	v_mfma_f32_16x16x32_bf16 v[52:55], v[148:151], v[182:185], v[52:55]
	v_mfma_f32_16x16x32_bf16 v[48:51], v[168:171], v[182:185], v[48:51]
	v_mfma_f32_16x16x32_bf16 v[36:39], v[148:151], v[190:193], v[36:39]
	v_mfma_f32_16x16x32_bf16 v[32:35], v[168:171], v[190:193], v[32:35]
	s_barrier
	v_mfma_f32_16x16x32_bf16 v[20:23], v[148:151], v[198:201], v[20:23]
	v_mfma_f32_16x16x32_bf16 v[16:19], v[168:171], v[198:201], v[16:19]
	v_mfma_f32_16x16x32_bf16 v[4:7], v[148:151], v[206:209], v[4:7]
	v_mfma_f32_16x16x32_bf16 v[0:3], v[168:171], v[206:209], v[0:3]
	s_setprio 0
	s_add_i32 s61, s61, 2
	s_add_u32 s22, s22, 0x100
	s_addc_u32 s23, s23, 0
	s_add_u32 s59, s59, 0x100
	s_addc_u32 s60, s60, 0
	s_cmp_gt_u32 s61, 13
	s_cbranch_scc0 .LBB0_1236
	s_and_b64 vcc, exec, s[12:13]
	s_cbranch_vccz .LBB0_1239
	s_barrier
